# DSA unit prologue: the wait before the first barrier no longer covers the first two Q loads (K tile 0 is already complete by the mask wait)
# speedup vs baseline: 1.0041x; 1.0041x over previous
; #define WAIT_BAR(N) asm volatile("s_waitcnt vmcnt(" #N ") lgkmcnt(0)\n\ts_barrier":::"memory")
;   #define DMA_K(t,slot) glds16(ksrc+(long)(t)*KVBLK*KP,(unsigned)__builtin_amdgcn_readfirstlane(kdst+(slot)))
;   #define DMA_V(t,slot) glds16(vsrc+(long)(t)*KVBLK*VP,(unsigned)__builtin_amdgcn_readfirstlane(vdst+(slot)))
;   #define XMASK(P0,P1,t) do{ if constexpr(MASKED){ bmask(P0,P1,mimg[(2*(t))*32],mimg[(2*(t)+1)*32],hi); } else { CMASK(P0,P1,t); } }while(0)
;     ...
;   DMA_K(0,0);DMA_V(0,0);DMA_K(1,SLOTB);
;   if constexpr(MASKED){
;     __attribute__((address_space(3))) u32x4* mdst=(__attribute__((address_space(3))) u32x4*)(shm3+LDS_OST+wid*MWAVE)+lane;
;     for(int i=0;i<=qb;++i){ const u32x4 v=((const u32x4*)mwave)[i*64+lane]; mdst[i*64]=v; }
;   }
;   bf16x8 qr[4];
;   #pragma unroll
;   for(int d0=0;d0<4;++d0)qr[d0]=*reinterpret_cast<const bf16x8*>(&Qw[(long)r32*QP+d0*16+hi*8]);
;   float mhat=0.f,l_reg=0.f;f32x16 o[2];o[0]=f32x16{};o[1]=f32x16{};f32x16 negm=f32x16{};asm volatile("":"+v"(negm));
;   const int qrel=wid*QBLK+r32;
;     ...
;   bool resc=false;
;     ...
;   f32x16 pA0,pA1,pB0,pB1;
;   int sl_prev=0,sl_cur=0,sl_next=SLOTB;
;     ...
;   DMA_K(2,2*SLOTB);
;   WAIT_BAR(3);
;   qkt(pA0,pA1,Kbase,qr,negm,r32,hi);asm volatile("s_nop 15\n\ts_nop 7":"+v"(pA0),"+v"(pA1));XMASK(pA0,pA1,0);
;   START(pA0,pA1);
;   _Pragma("unroll") for(int r=0;r<16;++r)pA1[r]=__builtin_amdgcn_exp2f(pA1[r]);
;   WAIT_BAR(0);
.LBB0_1521:
	v_mov_b32_e32 v14, v1
	v_mov_b32_e32 v15, v1
	v_mov_b32_e32 v0, v1
	v_mov_b32_e32 v2, v1
	v_mov_b32_e32 v3, v1
	v_mov_b32_e32 v4, v1
	v_mov_b32_e32 v5, v1
	v_mov_b32_e32 v6, v1
	v_mov_b32_e32 v7, v1
	v_mov_b32_e32 v8, v1
	v_mov_b32_e32 v9, v1
	v_mov_b32_e32 v10, v1
	v_mov_b32_e32 v11, v1
	v_mov_b32_e32 v12, v1
	v_mov_b32_e32 v13, v1
	v_mov_b64_e32 v[62:63], v[14:15]
	v_mov_b64_e32 v[60:61], v[12:13]
	v_mov_b64_e32 v[58:59], v[10:11]
	v_mov_b64_e32 v[56:57], v[8:9]
	v_mov_b64_e32 v[54:55], v[6:7]
	v_mov_b64_e32 v[52:53], v[4:5]
	v_mov_b64_e32 v[50:51], v[2:3]
	v_mov_b64_e32 v[48:49], v[0:1]
	v_lshl_add_u64 v[64:65], v[44:45], 0, s[20:21]
	v_lshlrev_b32_e32 v66, 10, v43
	v_lshlrev_b32_e32 v67, 4, v215
	s_add_i32 s0, s48, 0x4000
	s_mov_b32 s1, m0
	s_mov_b32 m0, s0
	s_nop 0
	global_load_lds_dwordx4 v[64:65], off
	s_mov_b32 m0, s1
	v_add3_u32 v227, 0, v66, v67
	s_waitcnt vmcnt(5) lgkmcnt(0)
	s_barrier
	ds_read_b128 v[2:5], v227
	ds_read_b128 v[6:9], v227 offset:512
	v_lshl_add_u32 v223, v215, 2, s46
	v_lshlrev_b32_e32 v0, 1, v42
	v_lshlrev_b32_e32 v10, 4, v42
	v_and_b32_e32 v221, 32, v0
	v_lshlrev_b32_e32 v0, 8, v43
	v_lshlrev_b32_e32 v224, 2, v43
	v_and_or_b32 v220, v10, s73, v0
	s_lshl_b32 s0, s22, 2
	s_add_i32 s47, s0, 0
	v_lshlrev_b32_e32 v210, 2, v215
	s_mov_b32 s8, 1
	s_mov_b32 s34, 0
	s_movk_i32 s44, 0x4000
	s_lshr_b32 s50, s29, 6
	s_movk_i32 s51, 0x2000
	s_and_b64 vcc, exec, s[2:3]
	v_cmp_gt_u32_e64 s[2:3], 32, v46
	v_add_u32_e32 v228, s47, v210
	v_lshl_add_u32 v222, v224, 2, s47
	s_waitcnt vmcnt(1) lgkmcnt(0)
	v_mfma_f32_32x32x16_bf16 v[64:79], v[2:5], v[166:169], v[48:63]
	v_mfma_f32_32x32x16_bf16 v[48:63], v[6:9], v[166:169], v[48:63]
	ds_read_b128 v[2:5], v227 offset:2048
	ds_read_b128 v[6:9], v227 offset:2560
	s_waitcnt lgkmcnt(1)
	v_mfma_f32_32x32x16_bf16 v[64:79], v[2:5], v[162:165], v[64:79]
	s_waitcnt lgkmcnt(0)
	v_mfma_f32_32x32x16_bf16 v[48:63], v[6:9], v[162:165], v[48:63]
	ds_read_b128 v[2:5], v227 offset:4096
	ds_read_b128 v[6:9], v227 offset:4608
	s_waitcnt lgkmcnt(1)
	v_mfma_f32_32x32x16_bf16 v[64:79], v[2:5], v[36:39], v[64:79]
	ds_read_b128 v[2:5], v227 offset:6144
	s_waitcnt lgkmcnt(1)
	v_mfma_f32_32x32x16_bf16 v[48:63], v[6:9], v[36:39], v[48:63]
	ds_read_b128 v[6:9], v227 offset:6656
	s_waitcnt lgkmcnt(1)
	v_mfma_f32_32x32x16_bf16 v[64:79], v[2:5], v[32:35], v[64:79]
	v_add_u32_e32 v2, 0xc800, v223
	v_add_u32_e32 v4, 0, v221
	v_add3_u32 v226, v4, v219, v220
	s_waitcnt lgkmcnt(0)
	v_mfma_f32_32x32x16_bf16 v[48:63], v[6:9], v[32:35], v[48:63]
	s_nop 15
	s_nop 7
	ds_read2_b32 v[2:3], v2 offset1:32
	s_waitcnt lgkmcnt(0)
	v_lshrrev_b32_e32 v2, v224, v2
	v_bfe_i32 v4, v2, 0, 1
	v_lshrrev_b32_e32 v3, v224, v3
	v_bfi_b32 v64, v4, v64, v47
	v_bfe_i32 v4, v3, 24, 1
	v_bfe_i32 v5, v3, 0, 1
	v_bfe_i32 v6, v2, 1, 1
	v_bfe_i32 v8, v2, 2, 1
	v_bfe_i32 v10, v2, 3, 1
	v_bfe_i32 v12, v2, 8, 1
	s_nop 0
	v_bfi_b32 v60, v4, v60, v47
	v_bfe_i32 v4, v2, 25, 1
	v_bfe_i32 v14, v2, 9, 1
	v_bfe_i32 v42, v2, 10, 1
	v_bfe_i32 v80, v2, 11, 1
	v_bfe_i32 v82, v2, 16, 1
	v_bfe_i32 v84, v2, 17, 1
	v_bfe_i32 v86, v2, 18, 1
	v_bfe_i32 v88, v2, 19, 1
	v_bfe_i32 v90, v2, 24, 1
	v_bfi_b32 v48, v5, v48, v47
	v_bfe_i32 v5, v3, 25, 1
	s_nop 0
	v_bfi_b32 v77, v4, v77, v47
	v_bfe_i32 v4, v2, 26, 1
	v_bfe_i32 v2, v2, 27, 1
	v_bfe_i32 v7, v3, 1, 1
	v_bfe_i32 v9, v3, 2, 1
	v_bfe_i32 v11, v3, 3, 1
	v_bfe_i32 v13, v3, 8, 1
	v_bfe_i32 v15, v3, 9, 1
	v_bfe_i32 v43, v3, 10, 1
	v_bfe_i32 v81, v3, 11, 1
	v_bfe_i32 v83, v3, 16, 1
	v_bfe_i32 v85, v3, 17, 1
	v_bfe_i32 v87, v3, 18, 1
	v_bfe_i32 v89, v3, 19, 1
	v_bfi_b32 v65, v6, v65, v47
	v_bfi_b32 v61, v5, v61, v47
	v_bfe_i32 v5, v3, 26, 1
	v_bfe_i32 v3, v3, 27, 1
	s_nop 0
	v_bfi_b32 v79, v2, v79, v47
	v_bfi_b32 v49, v7, v49, v47
	v_max3_f32 v2, v64, v65, v48
	v_bfi_b32 v66, v8, v66, v47
	v_bfi_b32 v50, v9, v50, v47
	v_bfi_b32 v67, v10, v67, v47
	v_bfi_b32 v51, v11, v51, v47
	v_bfi_b32 v63, v3, v63, v47
	v_bfi_b32 v68, v12, v68, v47
	v_bfi_b32 v69, v14, v69, v47
	v_bfi_b32 v70, v42, v70, v47
	s_nop 0
	v_max3_f32 v3, v66, v67, v49
	v_max3_f32 v2, v2, v50, v51
	v_bfi_b32 v71, v80, v71, v47
	v_bfi_b32 v52, v13, v52, v47
	v_bfi_b32 v53, v15, v53, v47
	v_bfi_b32 v54, v43, v54, v47
	v_bfi_b32 v55, v81, v55, v47
	s_nop 0
	v_max3_f32 v2, v2, v68, v69
	v_max3_f32 v3, v3, v70, v71
	v_bfi_b32 v72, v82, v72, v47
	v_bfi_b32 v73, v84, v73, v47
	v_bfi_b32 v74, v86, v74, v47
	v_bfi_b32 v75, v88, v75, v47
	s_nop 0
	v_max3_f32 v2, v2, v52, v53
	v_max3_f32 v3, v3, v54, v55
	v_bfi_b32 v56, v83, v56, v47
	v_bfi_b32 v57, v85, v57, v47
	v_bfi_b32 v58, v87, v58, v47
	v_bfi_b32 v59, v89, v59, v47
	s_nop 0
	v_max3_f32 v2, v2, v72, v73
	v_max3_f32 v3, v3, v74, v75
	v_bfi_b32 v76, v90, v76, v47
	v_bfi_b32 v78, v4, v78, v47
	v_bfi_b32 v62, v5, v62, v47
	s_nop 0
	v_max3_f32 v2, v2, v56, v57
	v_max3_f32 v3, v3, v58, v59
	s_nop 0
	v_max3_f32 v2, v2, v76, v77
	v_max3_f32 v3, v3, v78, v79
	s_nop 0
	v_max3_f32 v2, v2, v60, v61
	v_max3_f32 v3, v3, v62, v63
	s_nop 0
	v_max_f32_e32 v2, v2, v3
	s_nop 0
	v_mov_b32_e32 v3, v2
	s_nop 1
	v_permlane32_swap_b32_e32 v2, v3
	v_max_f32_e32 v2, v2, v3
	s_nop 0
	v_max_f32_e32 v2, v2, v2
	v_max_f32_e32 v2, 0xc1f00000, v2
	v_add_f32_e32 v225, v1, v2
	v_sub_f32_e32 v3, v64, v2
	v_sub_f32_e32 v4, v48, v2
	v_sub_f32_e32 v5, v65, v2
	v_sub_f32_e32 v6, v49, v2
	v_sub_f32_e32 v7, v66, v2
	s_nop 0
	v_xor_b32_e32 v80, 0x80000000, v225
	v_mov_b32_e32 v81, v80
	v_mov_b32_e32 v82, v80
	v_mov_b32_e32 v83, v80
	v_mov_b32_e32 v84, v80
	v_mov_b32_e32 v85, v80
	v_mov_b32_e32 v86, v80
	v_mov_b32_e32 v87, v80
	v_mov_b32_e32 v88, v80
	v_mov_b32_e32 v89, v80
	v_mov_b32_e32 v90, v80
	v_mov_b32_e32 v91, v80
	v_mov_b32_e32 v92, v80
	v_mov_b32_e32 v93, v80
	v_mov_b32_e32 v94, v80
	v_mov_b32_e32 v95, v80
	v_sub_f32_e32 v8, v50, v2
	v_sub_f32_e32 v9, v67, v2
	v_sub_f32_e32 v10, v51, v2
	v_sub_f32_e32 v11, v68, v2
	v_sub_f32_e32 v12, v52, v2
	v_sub_f32_e32 v13, v69, v2
	v_sub_f32_e32 v14, v53, v2
	v_sub_f32_e32 v15, v70, v2
	v_sub_f32_e32 v42, v54, v2
	v_sub_f32_e32 v43, v71, v2
	v_sub_f32_e32 v48, v55, v2
	v_sub_f32_e32 v49, v72, v2
	v_sub_f32_e32 v50, v56, v2
	v_sub_f32_e32 v51, v73, v2
	v_sub_f32_e32 v52, v57, v2
	v_sub_f32_e32 v53, v74, v2
	v_sub_f32_e32 v54, v58, v2
	v_sub_f32_e32 v55, v75, v2
	v_sub_f32_e32 v56, v59, v2
	v_sub_f32_e32 v57, v76, v2
	v_sub_f32_e32 v58, v60, v2
	v_sub_f32_e32 v59, v77, v2
	v_sub_f32_e32 v60, v61, v2
	v_sub_f32_e32 v61, v78, v2
	v_sub_f32_e32 v62, v62, v2
	v_sub_f32_e32 v64, v79, v2
	v_sub_f32_e32 v2, v63, v2
	s_waitcnt vmcnt(0) lgkmcnt(0)
	s_barrier
; #define WAIT_BAR(N) asm volatile("s_waitcnt vmcnt(" #N ") lgkmcnt(0)\n\ts_barrier":::"memory")
;   #define DMA_K(t,slot) glds16(ksrc+(long)(t)*KVBLK*KP,(unsigned)__builtin_amdgcn_readfirstlane(kdst+(slot)))
;   #define DMA_V(t,slot) glds16(vsrc+(long)(t)*KVBLK*VP,(unsigned)__builtin_amdgcn_readfirstlane(vdst+(slot)))
;   #define XMASK(P0,P1,t) do{ if constexpr(MASKED){ bmask(P0,P1,mimg[(2*(t))*32],mimg[(2*(t)+1)*32],hi); } else { CMASK(P0,P1,t); } }while(0)
;   #define ROT() do{sl_prev=sl_cur;sl_cur=sl_next;sl_next=(sl_next==(NSLOT-1)*SLOTB)?0:sl_next+SLOTB;}while(0)
;     ...
;   qkt(pA0,pA1,Kbase,qr,negm,r32,hi);asm volatile("s_nop 15\n\ts_nop 7":"+v"(pA0),"+v"(pA1));XMASK(pA0,pA1,0);
;   START(pA0,pA1);
;   _Pragma("unroll") for(int r=0;r<16;++r)pA1[r]=__builtin_amdgcn_exp2f(pA1[r]);
;   WAIT_BAR(0);
;   DMA_K(3,0);DMA_V(1,SLOTB);
;   ROT();
;   kload8(kf,kp0+sl_cur);
;   WAIT_BAR(2);
;   s16x4 vlo[8],vhi[8]; u32x4 pw0,pw1,pw2,pw3;
;     ...
;   int t=1;
;     ...
;   for(;t+5<NT;t+=2){
	v_exp_f32_e32 v112, v3
	v_exp_f32_e32 v111, v2
	v_lshl_add_u64 v[2:3], v[44:45], 0, s[52:53]
	s_mov_b32 s0, m0
	s_mov_b32 m0, s48
	s_nop 0
	global_load_lds_dwordx4 v[2:3], off
	s_mov_b32 m0, s0
	v_exp_f32_e32 v118, v15
	v_exp_f32_e32 v101, v14
	v_lshl_add_u64 v[14:15], v[40:41], 0, s[18:19]
	s_add_i32 s0, s49, 0x2000
	s_mov_b32 s1, m0
	s_mov_b32 m0, s0
	s_nop 0
	global_load_lds_dwordx4 v[14:15], off
	s_mov_b32 m0, s1
	ds_read_b128 v[198:201], v227 offset:8192
	ds_read_b128 v[194:197], v227 offset:8704
	ds_read_b128 v[190:193], v227 offset:10240
	ds_read_b128 v[186:189], v227 offset:10752
	ds_read_b128 v[182:185], v227 offset:12288
	ds_read_b128 v[178:181], v227 offset:12800
	ds_read_b128 v[174:177], v227 offset:14336
	ds_read_b128 v[170:173], v227 offset:14848
	v_exp_f32_e32 v113, v5
	v_exp_f32_e32 v114, v7
	v_exp_f32_e32 v115, v9
	v_exp_f32_e32 v116, v11
	v_exp_f32_e32 v117, v13
	v_exp_f32_e32 v119, v43
	v_exp_f32_e32 v120, v49
	v_exp_f32_e32 v121, v51
	v_exp_f32_e32 v122, v53
	v_exp_f32_e32 v123, v55
	v_exp_f32_e32 v124, v57
	v_exp_f32_e32 v125, v59
	v_exp_f32_e32 v126, v61
	v_exp_f32_e32 v127, v64
	v_exp_f32_e32 v96, v4
	v_exp_f32_e32 v97, v6
	v_exp_f32_e32 v98, v8
	v_exp_f32_e32 v99, v10
	v_exp_f32_e32 v100, v12
	v_exp_f32_e32 v102, v42
	v_exp_f32_e32 v103, v48
	v_exp_f32_e32 v104, v50
	v_exp_f32_e32 v105, v52
	v_exp_f32_e32 v106, v54
	v_exp_f32_e32 v107, v56
	v_exp_f32_e32 v108, v58
	v_exp_f32_e32 v109, v60
	v_exp_f32_e32 v110, v62
	s_waitcnt vmcnt(2) lgkmcnt(0)
	s_barrier
	s_cbranch_vccz .LBB0_1532
	s_mov_b64 s[0:1], 0xa000
	v_lshl_add_u64 v[208:209], v[44:45], 0, s[0:1]
	s_add_i32 s0, s46, 0xc900
	v_mov_b32_e32 v128, 0
	s_add_i32 s22, s50, -5
	v_lshl_add_u64 v[206:207], v[40:41], 0, s[52:53]
	v_add_u32_e32 v129, s0, v210
	s_movk_i32 s34, 0x4000
	s_movk_i32 s23, 0x2000
	s_mov_b32 s0, 0
	v_mov_b32_e32 v48, 0
	v_mov_b32_e32 v49, v128
	v_mov_b32_e32 v50, v128
	v_mov_b32_e32 v51, v128
	v_mov_b32_e32 v52, v128
	v_mov_b32_e32 v53, v128
	v_mov_b32_e32 v54, v128
	v_mov_b32_e32 v55, v128
	v_mov_b32_e32 v56, v128
	v_mov_b32_e32 v57, v128
	v_mov_b32_e32 v58, v128
	v_mov_b32_e32 v59, v128
	v_mov_b32_e32 v60, v128
	v_mov_b32_e32 v61, v128
	v_mov_b32_e32 v62, v128
	v_mov_b32_e32 v63, v128
	v_mov_b32_e32 v64, 0
	v_mov_b32_e32 v65, v128
	v_mov_b32_e32 v66, v128
	v_mov_b32_e32 v67, v128
	v_mov_b32_e32 v68, v128
	v_mov_b32_e32 v69, v128
	v_mov_b32_e32 v70, v128
	v_mov_b32_e32 v71, v128
	v_mov_b32_e32 v72, v128
	v_mov_b32_e32 v73, v128
	v_mov_b32_e32 v74, v128
	v_mov_b32_e32 v75, v128
	v_mov_b32_e32 v76, v128
	v_mov_b32_e32 v77, v128
	v_mov_b32_e32 v78, v128
	v_mov_b32_e32 v79, v128
